# P6b boundary-row phase: all 48 loads of a thread's six items in flight at once (was two batches with the second batch's waits behind the first batch's write-through store acks)
# speedup vs baseline: 1.0081x; 1.0034x over previous
; __device__ __forceinline__ unsigned cvt_pk_bf16(float lo, float hi) { unsigned r; asm volatile("v_cvt_pk_bf16_f32 %0, %1, %2" : "=v"(r) : "v"(lo), "v"(hi)); return r; }
; __global__ void __launch_bounds__(NTHR, 2) hybrid_block_fwd(Args a) {
;     ...
;         for (int idx = gtid; idx < 256 * 2 * (FF / 4); idx += NT) {
;             const int f4 = (idx % (FF / 4)) * 4, rr = (idx / (FF / 4)) & 1, blk = idx / (2 * (FF / 4));
;             const bool seq0 = (blk & 127) == 0; const size_t row = (size_t)blk * 64 + rr;
;             const f32x4 z = (f32x4){0.f, 0.f, 0.f, 0.f};
;             const f32x4 gc = *(const f32x4*)(HEADG + ((size_t)blk * 2 + rr) * FF + f4), vv = *(const f32x4*)(HEADV + ((size_t)blk * 2 + rr) * FF + f4);
;             f32x4 p1, p2;
;             if (rr == 0) { p1 = seq0 ? z : *(const f32x4*)(TAILG + ((size_t)(blk - 1) * 2 + 1) * FF + f4); p2 = seq0 ? z : *(const f32x4*)(TAILG + ((size_t)(blk - 1) * 2 + 0) * FF + f4); }
;             else { p1 = *(const f32x4*)(HEADG + ((size_t)blk * 2 + 0) * FF + f4); p2 = seq0 ? z : *(const f32x4*)(TAILG + ((size_t)(blk - 1) * 2 + 1) * FF + f4); }
;             const f32x4 cv = *(const f32x4*)(ffn_conv_b + f4) + *(const f32x4*)(ffn_conv_w + f4) * p2 + *(const f32x4*)(ffn_conv_w + FF + f4) * p1 + *(const f32x4*)(ffn_conv_w + 2 * FF + f4) * gc;
;             u32x2 w; w.x = cvt_pk_bf16(gelu_tanh(cv[0]) * vv[0], gelu_tanh(cv[1]) * vv[1]); w.y = cvt_pk_bf16(gelu_tanh(cv[2]) * vv[2], gelu_tanh(cv[3]) * vv[3]);
;             *(u32x2*)(ACT + row * FF + f4) = w;
.LBB0_1002:
	s_or_b64 exec, exec, s[0:1]
	s_waitcnt lgkmcnt(0)
	v_mov_b32_e32 v0, v212
	v_readlane_b32 s0, v248, 8
	s_barrier
	s_mov_b64 s[4:5], exec
	v_add_u32_e32 v1, s0, v0
	s_mov_b32 s6, 0x2aaaaaab
	v_mul_hi_i32 v2, v1, s6
	v_ashrrev_i32_e32 v3, 8, v2
	v_lshlrev_b32_e32 v4, 4, v1
	v_mul_u32_u24_e32 v5, 0x6000, v3
	v_sub_u32_e32 v4, v4, v5
	v_mov_b32_e32 v49, v3
	v_add_u32_e32 v6, v5, v4
	v_add_u32_e32 v7, 0x2700000, v6
	global_load_dwordx4 v[16:19], v7, s[94:95]
	v_add_u32_e32 v7, 0x3300000, v6
	global_load_dwordx4 v[20:23], v7, s[94:95]
	v_and_b32_e32 v8, 1, v3
	v_max_i32_e32 v9, 1, v3
	v_add_u32_e32 v9, -1, v9
	v_mul_u32_u24_e32 v9, 0x6000, v9
	v_add_u32_e32 v9, v9, v4
	v_cmp_eq_u32_e32 vcc, 1, v8
	v_mov_b32_e32 v7, 0x1b00000
	v_mov_b32_e32 v5, 0x2700000
	v_cndmask_b32_e32 v7, v7, v5, vcc
	v_add_u32_e32 v7, v7, v9
	global_load_dwordx4 v[24:27], v7, s[94:95]
	v_max_i32_e32 v9, 2, v3
	v_add_u32_e32 v9, -2, v9
	v_mul_u32_u24_e32 v9, 0x6000, v9
	v_add_u32_e32 v9, v9, v4
	v_add_u32_e32 v9, 0x1b00000, v9
	global_load_dwordx4 v[28:31], v9, s[94:95]
	global_load_dwordx4 v[32:35], v4, s[86:87]
	global_load_dwordx4 v[36:39], v4, s[84:85]
	global_load_dwordx4 v[40:43], v4, s[16:17]
	global_load_dwordx4 v[44:47], v4, s[18:19]
	v_lshrrev_b32_e32 v5, 1, v3
	v_lshl_or_b32 v5, v5, 6, v8
	v_mul_u32_u24_e32 v5, 0x3000, v5
	v_lshrrev_b32_e32 v7, 1, v4
	v_add_u32_e32 v5, v5, v7
	v_add_u32_e32 v48, 0x12700000, v5
	v_add_u32_e32 v1, 0x20000, v1
	v_mul_hi_i32 v2, v1, s6
	v_ashrrev_i32_e32 v3, 8, v2
	v_lshlrev_b32_e32 v4, 4, v1
	v_mul_u32_u24_e32 v5, 0x6000, v3
	v_sub_u32_e32 v4, v4, v5
	v_mov_b32_e32 v83, v3
	v_add_u32_e32 v6, v5, v4
	v_add_u32_e32 v7, 0x2700000, v6
	global_load_dwordx4 v[50:53], v7, s[94:95]
	v_add_u32_e32 v7, 0x3300000, v6
	global_load_dwordx4 v[54:57], v7, s[94:95]
	v_and_b32_e32 v8, 1, v3
	v_max_i32_e32 v9, 1, v3
	v_add_u32_e32 v9, -1, v9
	v_mul_u32_u24_e32 v9, 0x6000, v9
	v_add_u32_e32 v9, v9, v4
	v_cmp_eq_u32_e32 vcc, 1, v8
	v_mov_b32_e32 v7, 0x1b00000
	v_mov_b32_e32 v5, 0x2700000
	v_cndmask_b32_e32 v7, v7, v5, vcc
	v_add_u32_e32 v7, v7, v9
	global_load_dwordx4 v[58:61], v7, s[94:95]
	v_max_i32_e32 v9, 2, v3
	v_add_u32_e32 v9, -2, v9
	v_mul_u32_u24_e32 v9, 0x6000, v9
	v_add_u32_e32 v9, v9, v4
	v_add_u32_e32 v9, 0x1b00000, v9
	global_load_dwordx4 v[62:65], v9, s[94:95]
	global_load_dwordx4 v[66:69], v4, s[86:87]
	global_load_dwordx4 v[70:73], v4, s[84:85]
	global_load_dwordx4 v[74:77], v4, s[16:17]
	global_load_dwordx4 v[78:81], v4, s[18:19]
	v_lshrrev_b32_e32 v5, 1, v3
	v_lshl_or_b32 v5, v5, 6, v8
	v_mul_u32_u24_e32 v5, 0x3000, v5
	v_lshrrev_b32_e32 v7, 1, v4
	v_add_u32_e32 v5, v5, v7
	v_add_u32_e32 v82, 0x12700000, v5
	v_add_u32_e32 v1, 0x20000, v1
	v_mul_hi_i32 v2, v1, s6
	v_ashrrev_i32_e32 v3, 8, v2
	v_lshlrev_b32_e32 v4, 4, v1
	v_mul_u32_u24_e32 v5, 0x6000, v3
	v_sub_u32_e32 v4, v4, v5
	v_mov_b32_e32 v117, v3
	v_add_u32_e32 v6, v5, v4
	v_add_u32_e32 v7, 0x2700000, v6
	global_load_dwordx4 v[84:87], v7, s[94:95]
	v_add_u32_e32 v7, 0x3300000, v6
	global_load_dwordx4 v[88:91], v7, s[94:95]
	v_and_b32_e32 v8, 1, v3
	v_max_i32_e32 v9, 1, v3
	v_add_u32_e32 v9, -1, v9
	v_mul_u32_u24_e32 v9, 0x6000, v9
	v_add_u32_e32 v9, v9, v4
	v_cmp_eq_u32_e32 vcc, 1, v8
	v_mov_b32_e32 v7, 0x1b00000
	v_mov_b32_e32 v5, 0x2700000
	v_cndmask_b32_e32 v7, v7, v5, vcc
	v_add_u32_e32 v7, v7, v9
	global_load_dwordx4 v[92:95], v7, s[94:95]
	v_max_i32_e32 v9, 2, v3
	v_add_u32_e32 v9, -2, v9
	v_mul_u32_u24_e32 v9, 0x6000, v9
	v_add_u32_e32 v9, v9, v4
	v_add_u32_e32 v9, 0x1b00000, v9
	global_load_dwordx4 v[96:99], v9, s[94:95]
	global_load_dwordx4 v[100:103], v4, s[86:87]
	global_load_dwordx4 v[104:107], v4, s[84:85]
	global_load_dwordx4 v[108:111], v4, s[16:17]
	global_load_dwordx4 v[112:115], v4, s[18:19]
	v_lshrrev_b32_e32 v5, 1, v3
	v_lshl_or_b32 v5, v5, 6, v8
	v_mul_u32_u24_e32 v5, 0x3000, v5
	v_lshrrev_b32_e32 v7, 1, v4
	v_add_u32_e32 v5, v5, v7
	v_add_u32_e32 v116, 0x12700000, v5
	v_add_u32_e32 v1, 0x20000, v1
	v_mul_hi_i32 v2, v1, s6
	v_ashrrev_i32_e32 v3, 8, v2
	v_lshlrev_b32_e32 v4, 4, v1
	v_mul_u32_u24_e32 v5, 0x6000, v3
	v_sub_u32_e32 v4, v4, v5
	v_mov_b32_e32 v151, v3
	v_add_u32_e32 v6, v5, v4
	v_add_u32_e32 v7, 0x2700000, v6
	global_load_dwordx4 v[118:121], v7, s[94:95]
	v_add_u32_e32 v7, 0x3300000, v6
	global_load_dwordx4 v[122:125], v7, s[94:95]
	v_and_b32_e32 v8, 1, v3
	v_max_i32_e32 v9, 1, v3
	v_add_u32_e32 v9, -1, v9
	v_mul_u32_u24_e32 v9, 0x6000, v9
	v_add_u32_e32 v9, v9, v4
	v_cmp_eq_u32_e32 vcc, 1, v8
	v_mov_b32_e32 v7, 0x1b00000
	v_mov_b32_e32 v5, 0x2700000
	v_cndmask_b32_e32 v7, v7, v5, vcc
	v_add_u32_e32 v7, v7, v9
	global_load_dwordx4 v[126:129], v7, s[94:95]
	v_max_i32_e32 v9, 2, v3
	v_add_u32_e32 v9, -2, v9
	v_mul_u32_u24_e32 v9, 0x6000, v9
	v_add_u32_e32 v9, v9, v4
	v_add_u32_e32 v9, 0x1b00000, v9
	global_load_dwordx4 v[130:133], v9, s[94:95]
	global_load_dwordx4 v[134:137], v4, s[86:87]
	global_load_dwordx4 v[138:141], v4, s[84:85]
	global_load_dwordx4 v[142:145], v4, s[16:17]
	global_load_dwordx4 v[146:149], v4, s[18:19]
	v_lshrrev_b32_e32 v5, 1, v3
	v_lshl_or_b32 v5, v5, 6, v8
	v_mul_u32_u24_e32 v5, 0x3000, v5
	v_lshrrev_b32_e32 v7, 1, v4
	v_add_u32_e32 v5, v5, v7
	v_add_u32_e32 v150, 0x12700000, v5
	v_add_u32_e32 v1, 0x20000, v1
	v_mul_hi_i32 v2, v1, s6
	v_ashrrev_i32_e32 v3, 8, v2
	v_lshlrev_b32_e32 v4, 4, v1
	v_mul_u32_u24_e32 v5, 0x6000, v3
	v_sub_u32_e32 v4, v4, v5
	v_mov_b32_e32 v185, v3
	v_add_u32_e32 v6, v5, v4
	v_add_u32_e32 v7, 0x2700000, v6
	global_load_dwordx4 v[152:155], v7, s[94:95]
	v_add_u32_e32 v7, 0x3300000, v6
	global_load_dwordx4 v[156:159], v7, s[94:95]
	v_and_b32_e32 v8, 1, v3
	v_max_i32_e32 v9, 1, v3
; __device__ __forceinline__ unsigned cvt_pk_bf16(float lo, float hi) { unsigned r; asm volatile("v_cvt_pk_bf16_f32 %0, %1, %2" : "=v"(r) : "v"(lo), "v"(hi)); return r; }
; __global__ void __launch_bounds__(NTHR, 2) hybrid_block_fwd(Args a) {
;     ...
;         for (int idx = gtid; idx < 256 * 2 * (FF / 4); idx += NT) {
;             const int f4 = (idx % (FF / 4)) * 4, rr = (idx / (FF / 4)) & 1, blk = idx / (2 * (FF / 4));
;             const bool seq0 = (blk & 127) == 0; const size_t row = (size_t)blk * 64 + rr;
;             const f32x4 z = (f32x4){0.f, 0.f, 0.f, 0.f};
;             const f32x4 gc = *(const f32x4*)(HEADG + ((size_t)blk * 2 + rr) * FF + f4), vv = *(const f32x4*)(HEADV + ((size_t)blk * 2 + rr) * FF + f4);
;             f32x4 p1, p2;
;             if (rr == 0) { p1 = seq0 ? z : *(const f32x4*)(TAILG + ((size_t)(blk - 1) * 2 + 1) * FF + f4); p2 = seq0 ? z : *(const f32x4*)(TAILG + ((size_t)(blk - 1) * 2 + 0) * FF + f4); }
;             else { p1 = *(const f32x4*)(HEADG + ((size_t)blk * 2 + 0) * FF + f4); p2 = seq0 ? z : *(const f32x4*)(TAILG + ((size_t)(blk - 1) * 2 + 1) * FF + f4); }
;             const f32x4 cv = *(const f32x4*)(ffn_conv_b + f4) + *(const f32x4*)(ffn_conv_w + f4) * p2 + *(const f32x4*)(ffn_conv_w + FF + f4) * p1 + *(const f32x4*)(ffn_conv_w + 2 * FF + f4) * gc;
;             u32x2 w; w.x = cvt_pk_bf16(gelu_tanh(cv[0]) * vv[0], gelu_tanh(cv[1]) * vv[1]); w.y = cvt_pk_bf16(gelu_tanh(cv[2]) * vv[2], gelu_tanh(cv[3]) * vv[3]);
;             *(u32x2*)(ACT + row * FF + f4) = w;
	v_add_u32_e32 v9, -1, v9
	v_mul_u32_u24_e32 v9, 0x6000, v9
	v_add_u32_e32 v9, v9, v4
	v_cmp_eq_u32_e32 vcc, 1, v8
	v_mov_b32_e32 v7, 0x1b00000
	v_mov_b32_e32 v5, 0x2700000
	v_cndmask_b32_e32 v7, v7, v5, vcc
	v_add_u32_e32 v7, v7, v9
	global_load_dwordx4 v[160:163], v7, s[94:95]
	v_max_i32_e32 v9, 2, v3
	v_add_u32_e32 v9, -2, v9
	v_mul_u32_u24_e32 v9, 0x6000, v9
	v_add_u32_e32 v9, v9, v4
	v_add_u32_e32 v9, 0x1b00000, v9
	global_load_dwordx4 v[164:167], v9, s[94:95]
	global_load_dwordx4 v[168:171], v4, s[86:87]
	global_load_dwordx4 v[172:175], v4, s[84:85]
	global_load_dwordx4 v[176:179], v4, s[16:17]
	global_load_dwordx4 v[180:183], v4, s[18:19]
	v_lshrrev_b32_e32 v5, 1, v3
	v_lshl_or_b32 v5, v5, 6, v8
	v_mul_u32_u24_e32 v5, 0x3000, v5
	v_lshrrev_b32_e32 v7, 1, v4
	v_add_u32_e32 v5, v5, v7
	v_add_u32_e32 v184, 0x12700000, v5
	v_add_u32_e32 v1, 0x20000, v1
	v_mul_hi_i32 v2, v1, s6
	v_ashrrev_i32_e32 v3, 8, v2
	v_lshlrev_b32_e32 v4, 4, v1
	v_mul_u32_u24_e32 v5, 0x6000, v3
	v_sub_u32_e32 v4, v4, v5
	v_mov_b32_e32 v225, v3
	v_add_u32_e32 v6, v5, v4
	v_add_u32_e32 v7, 0x2700000, v6
	global_load_dwordx4 v[186:189], v7, s[94:95]
	v_add_u32_e32 v7, 0x3300000, v6
	global_load_dwordx4 v[190:193], v7, s[94:95]
	v_and_b32_e32 v8, 1, v3
	v_max_i32_e32 v9, 1, v3
	v_add_u32_e32 v9, -1, v9
	v_mul_u32_u24_e32 v9, 0x6000, v9
	v_add_u32_e32 v9, v9, v4
	v_cmp_eq_u32_e32 vcc, 1, v8
	v_mov_b32_e32 v7, 0x1b00000
	v_mov_b32_e32 v5, 0x2700000
	v_cndmask_b32_e32 v7, v7, v5, vcc
	v_add_u32_e32 v7, v7, v9
	global_load_dwordx4 v[194:197], v7, s[94:95]
	v_max_i32_e32 v9, 2, v3
	v_add_u32_e32 v9, -2, v9
	v_mul_u32_u24_e32 v9, 0x6000, v9
	v_add_u32_e32 v9, v9, v4
	v_add_u32_e32 v9, 0x1b00000, v9
	global_load_dwordx4 v[198:201], v9, s[94:95]
	global_load_dwordx4 v[202:205], v4, s[86:87]
	global_load_dwordx4 v[206:209], v4, s[84:85]
	global_load_dwordx4 v[216:219], v4, s[16:17]
	global_load_dwordx4 v[220:223], v4, s[18:19]
	v_lshrrev_b32_e32 v5, 1, v3
	v_lshl_or_b32 v5, v5, 6, v8
	v_mul_u32_u24_e32 v5, 0x3000, v5
	v_lshrrev_b32_e32 v7, 1, v4
	v_add_u32_e32 v5, v5, v7
	v_add_u32_e32 v224, 0x12700000, v5
	v_add_u32_e32 v1, 0x20000, v1
	s_waitcnt vmcnt(40)
	v_lshrrev_b32_e32 v2, 1, v49
	v_and_b32_e32 v2, 0x7f, v2
	v_cmp_eq_u32_e32 vcc, 0, v2
	v_and_b32_e32 v3, 1, v49
	v_cmp_eq_u32_e64 s[8:9], 0, v3
	s_nop 1
	s_and_b64 s[8:9], s[8:9], vcc
	s_nop 1
	v_cndmask_b32_e64 v28, v28, 0, vcc
	v_cndmask_b32_e64 v24, v24, 0, s[8:9]
	v_cndmask_b32_e64 v29, v29, 0, vcc
	v_cndmask_b32_e64 v25, v25, 0, s[8:9]
	v_cndmask_b32_e64 v30, v30, 0, vcc
	v_cndmask_b32_e64 v26, v26, 0, s[8:9]
	v_cndmask_b32_e64 v31, v31, 0, vcc
	v_cndmask_b32_e64 v27, v27, 0, s[8:9]
	v_pk_fma_f32 v[30:31], v[30:31], v[38:39], v[34:35]
	v_pk_fma_f32 v[28:29], v[28:29], v[36:37], v[32:33]
	v_pk_fma_f32 v[26:27], v[26:27], v[42:43], v[30:31]
	v_pk_fma_f32 v[24:25], v[24:25], v[40:41], v[28:29]
	v_pk_fma_f32 v[18:19], v[18:19], v[46:47], v[26:27]
	v_pk_fma_f32 v[16:17], v[16:17], v[44:45], v[24:25]
	v_mul_f32_e32 v32, 0x3d922279, v16
	v_mul_f32_e32 v33, 0x3d922279, v17
	v_mul_f32_e32 v34, 0x3d922279, v18
	v_mul_f32_e32 v35, 0x3d922279, v19
	v_fmaak_f32 v32, v16, v32, 0x3fcc422a
	v_fmaak_f32 v33, v17, v33, 0x3fcc422a
	v_fmaak_f32 v34, v18, v34, 0x3fcc422a
	v_fmaak_f32 v35, v19, v35, 0x3fcc422a
	v_mul_f32_e32 v32, v16, v32
	v_mul_f32_e32 v33, v17, v33
	v_mul_f32_e32 v34, v18, v34
	v_mul_f32_e32 v35, v19, v35
	v_mul_f32_e32 v32, 0xbfb8aa3b, v32
	v_mul_f32_e32 v33, 0xbfb8aa3b, v33
	v_mul_f32_e32 v34, 0xbfb8aa3b, v34
	v_mul_f32_e32 v35, 0xbfb8aa3b, v35
	v_exp_f32_e32 v32, v32
	v_exp_f32_e32 v33, v33
	v_exp_f32_e32 v34, v34
	v_exp_f32_e32 v35, v35
	v_add_f32_e32 v32, 1.0, v32
	v_add_f32_e32 v33, 1.0, v33
	v_add_f32_e32 v34, 1.0, v34
	v_add_f32_e32 v35, 1.0, v35
	v_rcp_f32_e32 v32, v32
	v_rcp_f32_e32 v33, v33
	v_rcp_f32_e32 v34, v34
	v_rcp_f32_e32 v35, v35
	v_mul_f32_e32 v16, v16, v32
	v_mul_f32_e32 v17, v17, v33
	v_mul_f32_e32 v18, v18, v34
	v_mul_f32_e32 v19, v19, v35
	v_mul_f32_e32 v16, v20, v16
	v_mul_f32_e32 v17, v21, v17
	v_mul_f32_e32 v18, v22, v18
	v_mul_f32_e32 v19, v23, v19
	v_cvt_pk_bf16_f32 v16, v16, v17
	v_cvt_pk_bf16_f32 v17, v18, v19
	global_store_dwordx2 v48, v[16:17], s[94:95] sc1
	s_waitcnt vmcnt(33)
	v_lshrrev_b32_e32 v2, 1, v83
	v_and_b32_e32 v2, 0x7f, v2
	v_cmp_eq_u32_e32 vcc, 0, v2
	v_and_b32_e32 v3, 1, v83
	v_cmp_eq_u32_e64 s[8:9], 0, v3
	s_nop 1
	s_and_b64 s[8:9], s[8:9], vcc
	s_nop 1
	v_cndmask_b32_e64 v62, v62, 0, vcc
	v_cndmask_b32_e64 v58, v58, 0, s[8:9]
	v_cndmask_b32_e64 v63, v63, 0, vcc
	v_cndmask_b32_e64 v59, v59, 0, s[8:9]
	v_cndmask_b32_e64 v64, v64, 0, vcc
	v_cndmask_b32_e64 v60, v60, 0, s[8:9]
	v_cndmask_b32_e64 v65, v65, 0, vcc
	v_cndmask_b32_e64 v61, v61, 0, s[8:9]
	v_pk_fma_f32 v[64:65], v[64:65], v[72:73], v[68:69]
	v_pk_fma_f32 v[62:63], v[62:63], v[70:71], v[66:67]
	v_pk_fma_f32 v[60:61], v[60:61], v[76:77], v[64:65]
	v_pk_fma_f32 v[58:59], v[58:59], v[74:75], v[62:63]
	v_pk_fma_f32 v[52:53], v[52:53], v[80:81], v[60:61]
	v_pk_fma_f32 v[50:51], v[50:51], v[78:79], v[58:59]
	v_mul_f32_e32 v66, 0x3d922279, v50
	v_mul_f32_e32 v67, 0x3d922279, v51
	v_mul_f32_e32 v68, 0x3d922279, v52
	v_mul_f32_e32 v69, 0x3d922279, v53
	v_fmaak_f32 v66, v50, v66, 0x3fcc422a
	v_fmaak_f32 v67, v51, v67, 0x3fcc422a
	v_fmaak_f32 v68, v52, v68, 0x3fcc422a
	v_fmaak_f32 v69, v53, v69, 0x3fcc422a
	v_mul_f32_e32 v66, v50, v66
	v_mul_f32_e32 v67, v51, v67
	v_mul_f32_e32 v68, v52, v68
	v_mul_f32_e32 v69, v53, v69
	v_mul_f32_e32 v66, 0xbfb8aa3b, v66
	v_mul_f32_e32 v67, 0xbfb8aa3b, v67
	v_mul_f32_e32 v68, 0xbfb8aa3b, v68
	v_mul_f32_e32 v69, 0xbfb8aa3b, v69
	v_exp_f32_e32 v66, v66
	v_exp_f32_e32 v67, v67
	v_exp_f32_e32 v68, v68
	v_exp_f32_e32 v69, v69
	v_add_f32_e32 v66, 1.0, v66
	v_add_f32_e32 v67, 1.0, v67
	v_add_f32_e32 v68, 1.0, v68
	v_add_f32_e32 v69, 1.0, v69
	v_rcp_f32_e32 v66, v66
	v_rcp_f32_e32 v67, v67
	v_rcp_f32_e32 v68, v68
	v_rcp_f32_e32 v69, v69
	v_mul_f32_e32 v50, v50, v66
	v_mul_f32_e32 v51, v51, v67
	v_mul_f32_e32 v52, v52, v68
	v_mul_f32_e32 v53, v53, v69
	v_mul_f32_e32 v50, v54, v50
	v_mul_f32_e32 v51, v55, v51
	v_mul_f32_e32 v52, v56, v52
	v_mul_f32_e32 v53, v57, v53
	v_cvt_pk_bf16_f32 v50, v50, v51
	v_cvt_pk_bf16_f32 v51, v52, v53
	global_store_dwordx2 v82, v[50:51], s[94:95] sc1
	s_waitcnt vmcnt(26)
; __device__ __forceinline__ unsigned cvt_pk_bf16(float lo, float hi) { unsigned r; asm volatile("v_cvt_pk_bf16_f32 %0, %1, %2" : "=v"(r) : "v"(lo), "v"(hi)); return r; }
; __global__ void __launch_bounds__(NTHR, 2) hybrid_block_fwd(Args a) {
;     ...
;         for (int idx = gtid; idx < 256 * 2 * (FF / 4); idx += NT) {
;             const int f4 = (idx % (FF / 4)) * 4, rr = (idx / (FF / 4)) & 1, blk = idx / (2 * (FF / 4));
;             const bool seq0 = (blk & 127) == 0; const size_t row = (size_t)blk * 64 + rr;
;             const f32x4 z = (f32x4){0.f, 0.f, 0.f, 0.f};
;             const f32x4 gc = *(const f32x4*)(HEADG + ((size_t)blk * 2 + rr) * FF + f4), vv = *(const f32x4*)(HEADV + ((size_t)blk * 2 + rr) * FF + f4);
;             f32x4 p1, p2;
;             if (rr == 0) { p1 = seq0 ? z : *(const f32x4*)(TAILG + ((size_t)(blk - 1) * 2 + 1) * FF + f4); p2 = seq0 ? z : *(const f32x4*)(TAILG + ((size_t)(blk - 1) * 2 + 0) * FF + f4); }
;             else { p1 = *(const f32x4*)(HEADG + ((size_t)blk * 2 + 0) * FF + f4); p2 = seq0 ? z : *(const f32x4*)(TAILG + ((size_t)(blk - 1) * 2 + 1) * FF + f4); }
;             const f32x4 cv = *(const f32x4*)(ffn_conv_b + f4) + *(const f32x4*)(ffn_conv_w + f4) * p2 + *(const f32x4*)(ffn_conv_w + FF + f4) * p1 + *(const f32x4*)(ffn_conv_w + 2 * FF + f4) * gc;
;             u32x2 w; w.x = cvt_pk_bf16(gelu_tanh(cv[0]) * vv[0], gelu_tanh(cv[1]) * vv[1]); w.y = cvt_pk_bf16(gelu_tanh(cv[2]) * vv[2], gelu_tanh(cv[3]) * vv[3]);
;             *(u32x2*)(ACT + row * FF + f4) = w;
	v_lshrrev_b32_e32 v2, 1, v117
	v_and_b32_e32 v2, 0x7f, v2
	v_cmp_eq_u32_e32 vcc, 0, v2
	v_and_b32_e32 v3, 1, v117
	v_cmp_eq_u32_e64 s[8:9], 0, v3
	s_nop 1
	s_and_b64 s[8:9], s[8:9], vcc
	s_nop 1
	v_cndmask_b32_e64 v96, v96, 0, vcc
	v_cndmask_b32_e64 v92, v92, 0, s[8:9]
	v_cndmask_b32_e64 v97, v97, 0, vcc
	v_cndmask_b32_e64 v93, v93, 0, s[8:9]
	v_cndmask_b32_e64 v98, v98, 0, vcc
	v_cndmask_b32_e64 v94, v94, 0, s[8:9]
	v_cndmask_b32_e64 v99, v99, 0, vcc
	v_cndmask_b32_e64 v95, v95, 0, s[8:9]
	v_pk_fma_f32 v[98:99], v[98:99], v[106:107], v[102:103]
	v_pk_fma_f32 v[96:97], v[96:97], v[104:105], v[100:101]
	v_pk_fma_f32 v[94:95], v[94:95], v[110:111], v[98:99]
	v_pk_fma_f32 v[92:93], v[92:93], v[108:109], v[96:97]
	v_pk_fma_f32 v[86:87], v[86:87], v[114:115], v[94:95]
	v_pk_fma_f32 v[84:85], v[84:85], v[112:113], v[92:93]
	v_mul_f32_e32 v100, 0x3d922279, v84
	v_mul_f32_e32 v101, 0x3d922279, v85
	v_mul_f32_e32 v102, 0x3d922279, v86
	v_mul_f32_e32 v103, 0x3d922279, v87
	v_fmaak_f32 v100, v84, v100, 0x3fcc422a
	v_fmaak_f32 v101, v85, v101, 0x3fcc422a
	v_fmaak_f32 v102, v86, v102, 0x3fcc422a
	v_fmaak_f32 v103, v87, v103, 0x3fcc422a
	v_mul_f32_e32 v100, v84, v100
	v_mul_f32_e32 v101, v85, v101
	v_mul_f32_e32 v102, v86, v102
	v_mul_f32_e32 v103, v87, v103
	v_mul_f32_e32 v100, 0xbfb8aa3b, v100
	v_mul_f32_e32 v101, 0xbfb8aa3b, v101
	v_mul_f32_e32 v102, 0xbfb8aa3b, v102
	v_mul_f32_e32 v103, 0xbfb8aa3b, v103
	v_exp_f32_e32 v100, v100
	v_exp_f32_e32 v101, v101
	v_exp_f32_e32 v102, v102
	v_exp_f32_e32 v103, v103
	v_add_f32_e32 v100, 1.0, v100
	v_add_f32_e32 v101, 1.0, v101
	v_add_f32_e32 v102, 1.0, v102
	v_add_f32_e32 v103, 1.0, v103
	v_rcp_f32_e32 v100, v100
	v_rcp_f32_e32 v101, v101
	v_rcp_f32_e32 v102, v102
	v_rcp_f32_e32 v103, v103
	v_mul_f32_e32 v84, v84, v100
	v_mul_f32_e32 v85, v85, v101
	v_mul_f32_e32 v86, v86, v102
	v_mul_f32_e32 v87, v87, v103
	v_mul_f32_e32 v84, v88, v84
	v_mul_f32_e32 v85, v89, v85
	v_mul_f32_e32 v86, v90, v86
	v_mul_f32_e32 v87, v91, v87
	v_cvt_pk_bf16_f32 v84, v84, v85
	v_cvt_pk_bf16_f32 v85, v86, v87
	global_store_dwordx2 v116, v[84:85], s[94:95] sc1
	s_waitcnt vmcnt(19)
	v_lshrrev_b32_e32 v2, 1, v151
	v_and_b32_e32 v2, 0x7f, v2
	v_cmp_eq_u32_e32 vcc, 0, v2
	v_and_b32_e32 v3, 1, v151
	v_cmp_eq_u32_e64 s[8:9], 0, v3
	s_nop 1
	s_and_b64 s[8:9], s[8:9], vcc
	s_nop 1
	v_cndmask_b32_e64 v130, v130, 0, vcc
	v_cndmask_b32_e64 v126, v126, 0, s[8:9]
	v_cndmask_b32_e64 v131, v131, 0, vcc
	v_cndmask_b32_e64 v127, v127, 0, s[8:9]
	v_cndmask_b32_e64 v132, v132, 0, vcc
	v_cndmask_b32_e64 v128, v128, 0, s[8:9]
	v_cndmask_b32_e64 v133, v133, 0, vcc
	v_cndmask_b32_e64 v129, v129, 0, s[8:9]
	v_pk_fma_f32 v[132:133], v[132:133], v[140:141], v[136:137]
	v_pk_fma_f32 v[130:131], v[130:131], v[138:139], v[134:135]
	v_pk_fma_f32 v[128:129], v[128:129], v[144:145], v[132:133]
	v_pk_fma_f32 v[126:127], v[126:127], v[142:143], v[130:131]
	v_pk_fma_f32 v[120:121], v[120:121], v[148:149], v[128:129]
	v_pk_fma_f32 v[118:119], v[118:119], v[146:147], v[126:127]
	v_mul_f32_e32 v134, 0x3d922279, v118
	v_mul_f32_e32 v135, 0x3d922279, v119
	v_mul_f32_e32 v136, 0x3d922279, v120
	v_mul_f32_e32 v137, 0x3d922279, v121
	v_fmaak_f32 v134, v118, v134, 0x3fcc422a
	v_fmaak_f32 v135, v119, v135, 0x3fcc422a
	v_fmaak_f32 v136, v120, v136, 0x3fcc422a
	v_fmaak_f32 v137, v121, v137, 0x3fcc422a
	v_mul_f32_e32 v134, v118, v134
	v_mul_f32_e32 v135, v119, v135
	v_mul_f32_e32 v136, v120, v136
	v_mul_f32_e32 v137, v121, v137
	v_mul_f32_e32 v134, 0xbfb8aa3b, v134
	v_mul_f32_e32 v135, 0xbfb8aa3b, v135
	v_mul_f32_e32 v136, 0xbfb8aa3b, v136
	v_mul_f32_e32 v137, 0xbfb8aa3b, v137
	v_exp_f32_e32 v134, v134
	v_exp_f32_e32 v135, v135
	v_exp_f32_e32 v136, v136
	v_exp_f32_e32 v137, v137
	v_add_f32_e32 v134, 1.0, v134
	v_add_f32_e32 v135, 1.0, v135
	v_add_f32_e32 v136, 1.0, v136
	v_add_f32_e32 v137, 1.0, v137
	v_rcp_f32_e32 v134, v134
	v_rcp_f32_e32 v135, v135
	v_rcp_f32_e32 v136, v136
	v_rcp_f32_e32 v137, v137
	v_mul_f32_e32 v118, v118, v134
	v_mul_f32_e32 v119, v119, v135
	v_mul_f32_e32 v120, v120, v136
	v_mul_f32_e32 v121, v121, v137
	v_mul_f32_e32 v118, v122, v118
	v_mul_f32_e32 v119, v123, v119
	v_mul_f32_e32 v120, v124, v120
	v_mul_f32_e32 v121, v125, v121
	v_cvt_pk_bf16_f32 v118, v118, v119
	v_cvt_pk_bf16_f32 v119, v120, v121
	global_store_dwordx2 v150, v[118:119], s[94:95] sc1
	s_waitcnt vmcnt(12)
; __device__ __forceinline__ unsigned cvt_pk_bf16(float lo, float hi) { unsigned r; asm volatile("v_cvt_pk_bf16_f32 %0, %1, %2" : "=v"(r) : "v"(lo), "v"(hi)); return r; }
; __global__ void __launch_bounds__(NTHR, 2) hybrid_block_fwd(Args a) {
;     ...
;             const int f4 = (idx % (FF / 4)) * 4, rr = (idx / (FF / 4)) & 1, blk = idx / (2 * (FF / 4));
;             const bool seq0 = (blk & 127) == 0; const size_t row = (size_t)blk * 64 + rr;
;             const f32x4 z = (f32x4){0.f, 0.f, 0.f, 0.f};
;             const f32x4 gc = *(const f32x4*)(HEADG + ((size_t)blk * 2 + rr) * FF + f4), vv = *(const f32x4*)(HEADV + ((size_t)blk * 2 + rr) * FF + f4);
;             f32x4 p1, p2;
;             if (rr == 0) { p1 = seq0 ? z : *(const f32x4*)(TAILG + ((size_t)(blk - 1) * 2 + 1) * FF + f4); p2 = seq0 ? z : *(const f32x4*)(TAILG + ((size_t)(blk - 1) * 2 + 0) * FF + f4); }
;             else { p1 = *(const f32x4*)(HEADG + ((size_t)blk * 2 + 0) * FF + f4); p2 = seq0 ? z : *(const f32x4*)(TAILG + ((size_t)(blk - 1) * 2 + 1) * FF + f4); }
;             const f32x4 cv = *(const f32x4*)(ffn_conv_b + f4) + *(const f32x4*)(ffn_conv_w + f4) * p2 + *(const f32x4*)(ffn_conv_w + FF + f4) * p1 + *(const f32x4*)(ffn_conv_w + 2 * FF + f4) * gc;
;             u32x2 w; w.x = cvt_pk_bf16(gelu_tanh(cv[0]) * vv[0], gelu_tanh(cv[1]) * vv[1]); w.y = cvt_pk_bf16(gelu_tanh(cv[2]) * vv[2], gelu_tanh(cv[3]) * vv[3]);
;             *(u32x2*)(ACT + row * FF + f4) = w;
	v_lshrrev_b32_e32 v2, 1, v185
	v_and_b32_e32 v2, 0x7f, v2
	v_cmp_eq_u32_e32 vcc, 0, v2
	v_and_b32_e32 v3, 1, v185
	v_cmp_eq_u32_e64 s[8:9], 0, v3
	s_nop 1
	s_and_b64 s[8:9], s[8:9], vcc
	s_nop 1
	v_cndmask_b32_e64 v164, v164, 0, vcc
	v_cndmask_b32_e64 v160, v160, 0, s[8:9]
	v_cndmask_b32_e64 v165, v165, 0, vcc
	v_cndmask_b32_e64 v161, v161, 0, s[8:9]
	v_cndmask_b32_e64 v166, v166, 0, vcc
	v_cndmask_b32_e64 v162, v162, 0, s[8:9]
	v_cndmask_b32_e64 v167, v167, 0, vcc
	v_cndmask_b32_e64 v163, v163, 0, s[8:9]
	v_pk_fma_f32 v[166:167], v[166:167], v[174:175], v[170:171]
	v_pk_fma_f32 v[164:165], v[164:165], v[172:173], v[168:169]
	v_pk_fma_f32 v[162:163], v[162:163], v[178:179], v[166:167]
	v_pk_fma_f32 v[160:161], v[160:161], v[176:177], v[164:165]
	v_pk_fma_f32 v[154:155], v[154:155], v[182:183], v[162:163]
	v_pk_fma_f32 v[152:153], v[152:153], v[180:181], v[160:161]
	v_mul_f32_e32 v168, 0x3d922279, v152
	v_mul_f32_e32 v169, 0x3d922279, v153
	v_mul_f32_e32 v170, 0x3d922279, v154
	v_mul_f32_e32 v171, 0x3d922279, v155
	v_fmaak_f32 v168, v152, v168, 0x3fcc422a
	v_fmaak_f32 v169, v153, v169, 0x3fcc422a
	v_fmaak_f32 v170, v154, v170, 0x3fcc422a
	v_fmaak_f32 v171, v155, v171, 0x3fcc422a
	v_mul_f32_e32 v168, v152, v168
	v_mul_f32_e32 v169, v153, v169
	v_mul_f32_e32 v170, v154, v170
	v_mul_f32_e32 v171, v155, v171
	v_mul_f32_e32 v168, 0xbfb8aa3b, v168
	v_mul_f32_e32 v169, 0xbfb8aa3b, v169
	v_mul_f32_e32 v170, 0xbfb8aa3b, v170
	v_mul_f32_e32 v171, 0xbfb8aa3b, v171
	v_exp_f32_e32 v168, v168
	v_exp_f32_e32 v169, v169
	v_exp_f32_e32 v170, v170
	v_exp_f32_e32 v171, v171
	v_add_f32_e32 v168, 1.0, v168
	v_add_f32_e32 v169, 1.0, v169
	v_add_f32_e32 v170, 1.0, v170
	v_add_f32_e32 v171, 1.0, v171
	v_rcp_f32_e32 v168, v168
	v_rcp_f32_e32 v169, v169
	v_rcp_f32_e32 v170, v170
	v_rcp_f32_e32 v171, v171
	v_mul_f32_e32 v152, v152, v168
	v_mul_f32_e32 v153, v153, v169
	v_mul_f32_e32 v154, v154, v170
	v_mul_f32_e32 v155, v155, v171
	v_mul_f32_e32 v152, v156, v152
	v_mul_f32_e32 v153, v157, v153
	v_mul_f32_e32 v154, v158, v154
	v_mul_f32_e32 v155, v159, v155
	v_cvt_pk_bf16_f32 v152, v152, v153
	v_cvt_pk_bf16_f32 v153, v154, v155
	global_store_dwordx2 v184, v[152:153], s[94:95] sc1
	s_waitcnt vmcnt(5)
	v_lshrrev_b32_e32 v2, 1, v225
	v_and_b32_e32 v2, 0x7f, v2
	v_cmp_eq_u32_e32 vcc, 0, v2
	v_and_b32_e32 v3, 1, v225
	v_cmp_eq_u32_e64 s[8:9], 0, v3
	s_nop 1
	s_and_b64 s[8:9], s[8:9], vcc
	s_nop 1
	v_cndmask_b32_e64 v198, v198, 0, vcc
	v_cndmask_b32_e64 v194, v194, 0, s[8:9]
	v_cndmask_b32_e64 v199, v199, 0, vcc
	v_cndmask_b32_e64 v195, v195, 0, s[8:9]
	v_cndmask_b32_e64 v200, v200, 0, vcc
	v_cndmask_b32_e64 v196, v196, 0, s[8:9]
	v_cndmask_b32_e64 v201, v201, 0, vcc
	v_cndmask_b32_e64 v197, v197, 0, s[8:9]
	v_pk_fma_f32 v[200:201], v[200:201], v[208:209], v[204:205]
	v_pk_fma_f32 v[198:199], v[198:199], v[206:207], v[202:203]
	v_pk_fma_f32 v[196:197], v[196:197], v[218:219], v[200:201]
	v_pk_fma_f32 v[194:195], v[194:195], v[216:217], v[198:199]
	v_pk_fma_f32 v[188:189], v[188:189], v[222:223], v[196:197]
	v_pk_fma_f32 v[186:187], v[186:187], v[220:221], v[194:195]
	v_mul_f32_e32 v202, 0x3d922279, v186
	v_mul_f32_e32 v203, 0x3d922279, v187
	v_mul_f32_e32 v204, 0x3d922279, v188
	v_mul_f32_e32 v205, 0x3d922279, v189
	v_fmaak_f32 v202, v186, v202, 0x3fcc422a
	v_fmaak_f32 v203, v187, v203, 0x3fcc422a
	v_fmaak_f32 v204, v188, v204, 0x3fcc422a
	v_fmaak_f32 v205, v189, v205, 0x3fcc422a
	v_mul_f32_e32 v202, v186, v202
	v_mul_f32_e32 v203, v187, v203
	v_mul_f32_e32 v204, v188, v204
	v_mul_f32_e32 v205, v189, v205
	v_mul_f32_e32 v202, 0xbfb8aa3b, v202
	v_mul_f32_e32 v203, 0xbfb8aa3b, v203
	v_mul_f32_e32 v204, 0xbfb8aa3b, v204
	v_mul_f32_e32 v205, 0xbfb8aa3b, v205
	v_exp_f32_e32 v202, v202
	v_exp_f32_e32 v203, v203
	v_exp_f32_e32 v204, v204
	v_exp_f32_e32 v205, v205
	v_add_f32_e32 v202, 1.0, v202
	v_add_f32_e32 v203, 1.0, v203
	v_add_f32_e32 v204, 1.0, v204
	v_add_f32_e32 v205, 1.0, v205
	v_rcp_f32_e32 v202, v202
	v_rcp_f32_e32 v203, v203
	v_rcp_f32_e32 v204, v204
	v_rcp_f32_e32 v205, v205
	v_mul_f32_e32 v186, v186, v202
	v_mul_f32_e32 v187, v187, v203
	v_mul_f32_e32 v188, v188, v204
	v_mul_f32_e32 v189, v189, v205
	v_mul_f32_e32 v186, v190, v186
	v_mul_f32_e32 v187, v191, v187
	v_mul_f32_e32 v188, v192, v188
	v_mul_f32_e32 v189, v193, v189
	v_cvt_pk_bf16_f32 v186, v186, v187
	v_cvt_pk_bf16_f32 v187, v188, v189
	global_store_dwordx2 v224, v[186:187], s[94:95] sc1
	s_or_b64 exec, exec, s[4:5]
	s_waitcnt vmcnt(0)
	s_barrier
	v_readfirstlane_b32 s0, v212
	s_cmp_lg_u32 s0, 64
	s_cbranch_scc1 .Linv_8
	buffer_inv sc1
	s_waitcnt vmcnt(0)
